# attention loop: lgkmcnt waits coalesced (11 instead of 22 per key block) to cut issue slots
# baseline (speedup 1.0000x reference)
.LBB0_1326:
	s_mul_hi_u32 s34, s77, 0xaaaaaaab
	s_lshr_b32 s34, s34, 1
	s_mul_i32 s34, s34, 0xc000
	v_subrev_u32_e32 v0, s34, v130
	s_add_i32 s34, s2, s36
	v_add_u32_e32 v0, s34, v0
	ds_read_b128 v[188:191], v0
	ds_read_b128 v[82:85], v0 offset:4096
	ds_read_b128 v[94:97], v0 offset:6144
	ds_read_b128 v[98:101], v0 offset:1024
	ds_read_b128 v[86:89], v0 offset:2048
	ds_read_b128 v[132:135], v0 offset:3072
	s_waitcnt lgkmcnt(6)
	v_mfma_f32_16x16x32_bf16 v[30:33], v[204:207], v[14:17], v[30:33]
	v_mfma_f32_16x16x32_bf16 v[50:53], v[208:211], v[14:17], v[50:53]
	v_mfma_f32_16x16x32_bf16 v[42:45], v[212:215], v[14:17], v[42:45]
	v_mfma_f32_16x16x32_bf16 v[34:37], v[216:219], v[14:17], v[34:37]
	s_waitcnt lgkmcnt(5)
	v_mfma_f32_16x16x32_bf16 v[188:191], v[188:191], v[10:13], v[150:153]
	ds_read_b128 v[78:81], v0 offset:5120
	s_waitcnt lgkmcnt(2)
	v_mfma_f32_16x16x32_bf16 v[136:139], v[86:89], v[10:13], v[150:153]
	ds_read_b128 v[86:89], v0 offset:7168
	v_mfma_f32_16x16x32_bf16 v[90:93], v[82:85], v[10:13], v[150:153]
	v_mfma_f32_16x16x32_bf16 v[94:97], v[94:97], v[10:13], v[150:153]
	v_mfma_f32_16x16x32_bf16 v[160:163], v[98:101], v[18:21], v[188:191]
	s_waitcnt lgkmcnt(2)
	v_mfma_f32_16x16x32_bf16 v[164:167], v[132:135], v[18:21], v[136:139]
	s_mov_b32 s34, 0x41000000
	v_cmp_lt_f32_e32 vcc, s34, v194
	s_cmp_lg_u64 vcc, 0
	s_cselect_b64 s[34:35], -1, 0
	s_cbranch_vccz .LBB0_1328
	v_cndmask_b32_e32 v132, 0, v194, vcc
	v_exp_f32_e64 v0, -v132
	v_sub_f32_e32 v74, v74, v132
	v_sub_f32_e32 v75, v75, v132
	v_sub_f32_e32 v76, v76, v132
	v_sub_f32_e32 v77, v77, v132
	v_sub_f32_e32 v70, v70, v132
	v_sub_f32_e32 v71, v71, v132
	v_sub_f32_e32 v72, v72, v132
	v_sub_f32_e32 v73, v73, v132
	v_sub_f32_e32 v22, v22, v132
	v_sub_f32_e32 v23, v23, v132
	v_sub_f32_e32 v24, v24, v132
	v_sub_f32_e32 v25, v25, v132
	v_sub_f32_e32 v26, v26, v132
	v_sub_f32_e32 v27, v27, v132
	v_sub_f32_e32 v28, v28, v132
	v_sub_f32_e32 v29, v29, v132
	v_add_f32_e32 v113, v113, v132
	v_xor_b32_e32 v150, 0x80000000, v113
	v_mov_b32_e32 v151, v150
	v_mov_b32_e32 v152, v150
	v_mov_b32_e32 v153, v150
	s_branch .LBB0_1329
.LBB0_1328:
.LBB0_1329:
	s_waitcnt lgkmcnt(0)
	v_mfma_f32_16x16x32_bf16 v[168:171], v[78:81], v[18:21], v[90:93]
	ds_read_b128 v[78:81], v131 offset:57344
	v_mfma_f32_16x16x32_bf16 v[172:175], v[86:89], v[18:21], v[94:97]
	ds_read_b128 v[86:89], v131 offset:59392
	v_exp_f32_e32 v145, v74
	v_exp_f32_e32 v146, v75
	v_exp_f32_e32 v147, v76
	v_exp_f32_e32 v148, v77
	ds_read_b128 v[176:179], v131 offset:61440
	s_waitcnt lgkmcnt(2)
	v_mfma_f32_16x16x32_bf16 v[58:61], v[78:81], v[14:17], v[58:61]
	ds_read_b128 v[78:81], v131 offset:54272
	v_max3_f32 v195, v160, v161, v162
	v_max3_f32 v195, v195, v163, v164
	v_max3_f32 v195, v195, v165, v166
	v_max_f32_e32 v195, v195, v167
	ds_read_b128 v[82:85], v131 offset:63488
	s_waitcnt lgkmcnt(3)
	v_mfma_f32_16x16x32_bf16 v[54:57], v[86:89], v[14:17], v[54:57]
	ds_read_b128 v[86:89], v131 offset:56320
	s_cmp_ge_u32 s73, s71
	s_cbranch_scc1 .Latt_stgA_skip
	s_mul_hi_u32 s49, s50, 0xaaaaaaab
	s_lshr_b32 s49, s49, 1
	s_mul_i32 s49, s49, 0xc000
	s_sub_i32 s49, s31, s49
	s_add_i32 s49, s36, s49
	s_add_i32 s49, s2, s49
	s_lshl_b32 s51, s37, 14
	s_add_i32 s51, s76, s51
	s_mov_b32 m0, s49
	s_add_i32 s50, s51, 0xc000
	global_load_lds_dwordx4 v[114:115], off
	v_lshl_add_u64 v[192:193], v[114:115], 0, s[44:45]
	s_add_i32 m0, s49, 0x2000
	s_nop 0
	global_load_lds_dwordx4 v[192:193], off
	s_mov_b32 m0, s50
	s_nop 0
	global_load_lds_dwordx4 v[118:119], off
	s_add_i32 m0, s51, 0xe000
	s_nop 0
	global_load_lds_dwordx4 v[116:117], off
.Latt_stgA_skip:
	ds_read_b128 v[90:93], v131 offset:50176
	s_waitcnt lgkmcnt(1)
	v_mfma_f32_16x16x32_bf16 v[46:49], v[176:179], v[14:17], v[46:49]
	ds_read_b128 v[176:179], v131 offset:58368
	v_exp_f32_e32 v98, v70
	v_exp_f32_e32 v99, v71
	v_exp_f32_e32 v100, v72
	v_exp_f32_e32 v101, v73
	ds_read_b128 v[180:183], v131 offset:52224
	v_mfma_f32_16x16x32_bf16 v[38:41], v[82:85], v[14:17], v[38:41]
	v_max3_f32 v194, v168, v169, v170
	v_max3_f32 v194, v194, v171, v172
	v_max3_f32 v194, v194, v173, v174
	v_max3_f32 v194, v194, v175, v195
	v_mfma_f32_16x16x32_bf16 v[2:5], v[154:157], v[14:17], v[2:5]
	v_exp_f32_e32 v102, v22
	v_exp_f32_e32 v103, v23
	v_exp_f32_e32 v104, v24
	v_exp_f32_e32 v105, v25
	ds_read_b128 v[94:97], v131 offset:60416
	s_waitcnt lgkmcnt(2)
	v_mfma_f32_16x16x32_bf16 v[30:33], v[90:93], v[6:9], v[30:33]
	ds_read_b128 v[90:93], v131 offset:62464
	v_mov_b32_e32 v158, v194
	s_nop 1
	v_permlane16_swap_b32_e32 v194, v158
	v_max_f32_e32 v194, v194, v158
	s_waitcnt lgkmcnt(2)
	v_mfma_f32_16x16x32_bf16 v[50:53], v[180:183], v[6:9], v[50:53]
	ds_read_b128 v[180:183], v131 offset:64512
	v_exp_f32_e32 v133, v26
	v_exp_f32_e32 v134, v27
	v_exp_f32_e32 v135, v28
	v_exp_f32_e32 v136, v29
	v_mfma_f32_16x16x32_bf16 v[42:45], v[78:81], v[6:9], v[42:45]
	v_mov_b32_e32 v158, v194
	s_nop 1
	v_permlane32_swap_b32_e32 v194, v158
	v_max_f32_e32 v194, v194, v158
	v_mfma_f32_16x16x32_bf16 v[34:37], v[86:89], v[6:9], v[34:37]
	v_cvt_pk_bf16_f32 v14, v145, v146
	v_cvt_pk_bf16_f32 v15, v147, v148
	v_cvt_pk_bf16_f32 v16, v98, v99
	v_cvt_pk_bf16_f32 v17, v100, v101
	v_cvt_pk_bf16_f32 v184, v102, v103
	v_cvt_pk_bf16_f32 v185, v104, v105
	v_cvt_pk_bf16_f32 v186, v133, v134
	v_cvt_pk_bf16_f32 v187, v135, v136
	v_mfma_f32_16x16x32_bf16 v[58:61], v[176:179], v[6:9], v[58:61]
	s_waitcnt lgkmcnt(0)
	v_mfma_f32_16x16x32_bf16 v[54:57], v[94:97], v[6:9], v[54:57]
	v_mfma_f32_16x16x32_bf16 v[46:49], v[90:93], v[6:9], v[46:49]
	v_mfma_f32_16x16x32_bf16 v[38:41], v[180:183], v[6:9], v[38:41]
	v_mfma_f32_16x16x32_bf16 v[2:5], v[154:157], v[6:9], v[2:5]
	s_andn2_b64 vcc, exec, s[34:35]
	s_cbranch_vccnz .LBB0_1331
	v_sub_f32_e32 v160, v160, v132
	v_sub_f32_e32 v161, v161, v132
	v_sub_f32_e32 v162, v162, v132
	v_sub_f32_e32 v163, v163, v132
	v_sub_f32_e32 v164, v164, v132
	v_sub_f32_e32 v165, v165, v132
	v_sub_f32_e32 v166, v166, v132
	v_sub_f32_e32 v167, v167, v132
	v_sub_f32_e32 v168, v168, v132
	v_sub_f32_e32 v169, v169, v132
	v_sub_f32_e32 v170, v170, v132
	v_sub_f32_e32 v171, v171, v132
	v_sub_f32_e32 v172, v172, v132
	v_sub_f32_e32 v173, v173, v132
	v_sub_f32_e32 v174, v174, v132
	v_sub_f32_e32 v175, v175, v132
	v_sub_f32_e32 v194, v194, v132
	v_pk_mul_f32 v[40:41], v[0:1], v[40:41] op_sel_hi:[0,1]
	v_pk_mul_f32 v[48:49], v[0:1], v[48:49] op_sel_hi:[0,1]
	v_pk_mul_f32 v[56:57], v[0:1], v[56:57] op_sel_hi:[0,1]
	v_pk_mul_f32 v[60:61], v[0:1], v[60:61] op_sel_hi:[0,1]
	v_pk_mul_f32 v[36:37], v[0:1], v[36:37] op_sel_hi:[0,1]
	v_pk_mul_f32 v[44:45], v[0:1], v[44:45] op_sel_hi:[0,1]
	v_pk_mul_f32 v[52:53], v[0:1], v[52:53] op_sel_hi:[0,1]
	v_pk_mul_f32 v[32:33], v[0:1], v[32:33] op_sel_hi:[0,1]
	v_pk_mul_f32 v[38:39], v[0:1], v[38:39] op_sel_hi:[0,1]
	v_pk_mul_f32 v[46:47], v[0:1], v[46:47] op_sel_hi:[0,1]
	v_pk_mul_f32 v[54:55], v[0:1], v[54:55] op_sel_hi:[0,1]
	v_pk_mul_f32 v[58:59], v[0:1], v[58:59] op_sel_hi:[0,1]
	v_pk_mul_f32 v[34:35], v[0:1], v[34:35] op_sel_hi:[0,1]
	v_pk_mul_f32 v[42:43], v[0:1], v[42:43] op_sel_hi:[0,1]
	v_pk_mul_f32 v[50:51], v[0:1], v[50:51] op_sel_hi:[0,1]
	v_pk_mul_f32 v[30:31], v[0:1], v[30:31] op_sel_hi:[0,1]
	v_pk_mul_f32 v[4:5], v[0:1], v[4:5] op_sel_hi:[0,1]
	v_pk_mul_f32 v[2:3], v[0:1], v[2:3] op_sel_hi:[0,1]

.Latt_B_1326:
	s_mul_hi_u32 s34, s77, 0xaaaaaaab
	s_lshr_b32 s34, s34, 1
	s_mul_i32 s34, s34, 0xc000
	v_subrev_u32_e32 v0, s34, v130
	s_add_i32 s34, s2, s36
	v_add_u32_e32 v0, s34, v0
	ds_read_b128 v[188:191], v0
	ds_read_b128 v[82:85], v0 offset:4096
	ds_read_b128 v[94:97], v0 offset:6144
	ds_read_b128 v[98:101], v0 offset:1024
	ds_read_b128 v[86:89], v0 offset:2048
	ds_read_b128 v[132:135], v0 offset:3072
	s_waitcnt lgkmcnt(6)
	v_mfma_f32_16x16x32_bf16 v[30:33], v[204:207], v[14:17], v[30:33]
	v_mfma_f32_16x16x32_bf16 v[50:53], v[208:211], v[14:17], v[50:53]
	v_mfma_f32_16x16x32_bf16 v[42:45], v[212:215], v[14:17], v[42:45]
	v_mfma_f32_16x16x32_bf16 v[34:37], v[216:219], v[14:17], v[34:37]
	s_waitcnt lgkmcnt(5)
	v_mfma_f32_16x16x32_bf16 v[188:191], v[188:191], v[10:13], v[150:153]
	ds_read_b128 v[78:81], v0 offset:5120
	s_waitcnt lgkmcnt(2)
	v_mfma_f32_16x16x32_bf16 v[136:139], v[86:89], v[10:13], v[150:153]
	ds_read_b128 v[86:89], v0 offset:7168
	v_mfma_f32_16x16x32_bf16 v[90:93], v[82:85], v[10:13], v[150:153]
	v_mfma_f32_16x16x32_bf16 v[94:97], v[94:97], v[10:13], v[150:153]
	v_mfma_f32_16x16x32_bf16 v[74:77], v[98:101], v[18:21], v[188:191]
	s_waitcnt lgkmcnt(2)
	v_mfma_f32_16x16x32_bf16 v[70:73], v[132:135], v[18:21], v[136:139]
	s_mov_b32 s34, 0x41000000
	v_cmp_lt_f32_e32 vcc, s34, v194
	s_cmp_lg_u64 vcc, 0
	s_cselect_b64 s[34:35], -1, 0
	s_cbranch_vccz .Latt_B_1328
	v_cndmask_b32_e32 v132, 0, v194, vcc
	v_exp_f32_e64 v0, -v132
	v_sub_f32_e32 v160, v160, v132
	v_sub_f32_e32 v161, v161, v132
	v_sub_f32_e32 v162, v162, v132
	v_sub_f32_e32 v163, v163, v132
	v_sub_f32_e32 v164, v164, v132
	v_sub_f32_e32 v165, v165, v132
	v_sub_f32_e32 v166, v166, v132
	v_sub_f32_e32 v167, v167, v132
	v_sub_f32_e32 v168, v168, v132
	v_sub_f32_e32 v169, v169, v132
	v_sub_f32_e32 v170, v170, v132
	v_sub_f32_e32 v171, v171, v132
	v_sub_f32_e32 v172, v172, v132
	v_sub_f32_e32 v173, v173, v132
	v_sub_f32_e32 v174, v174, v132
	v_sub_f32_e32 v175, v175, v132
	v_add_f32_e32 v113, v113, v132
	v_xor_b32_e32 v150, 0x80000000, v113
	v_mov_b32_e32 v151, v150
	v_mov_b32_e32 v152, v150
	v_mov_b32_e32 v153, v150
	s_branch .Latt_B_1329
.Latt_B_1328:
.Latt_B_1329:
	s_waitcnt lgkmcnt(0)
	v_mfma_f32_16x16x32_bf16 v[22:25], v[78:81], v[18:21], v[90:93]
	ds_read_b128 v[78:81], v131 offset:57344
	v_mfma_f32_16x16x32_bf16 v[26:29], v[86:89], v[18:21], v[94:97]
	ds_read_b128 v[86:89], v131 offset:59392
	v_exp_f32_e32 v145, v160
	v_exp_f32_e32 v146, v161
	v_exp_f32_e32 v147, v162
	v_exp_f32_e32 v148, v163
	ds_read_b128 v[176:179], v131 offset:61440
	s_waitcnt lgkmcnt(2)
	v_mfma_f32_16x16x32_bf16 v[58:61], v[78:81], v[14:17], v[58:61]
	ds_read_b128 v[78:81], v131 offset:54272
	v_max3_f32 v195, v74, v75, v76
	v_max3_f32 v195, v195, v77, v70
	v_max3_f32 v195, v195, v71, v72
	v_max_f32_e32 v195, v195, v73
	ds_read_b128 v[82:85], v131 offset:63488
	s_waitcnt lgkmcnt(3)
	v_mfma_f32_16x16x32_bf16 v[54:57], v[86:89], v[14:17], v[54:57]
	ds_read_b128 v[86:89], v131 offset:56320
	s_cmp_ge_u32 s73, s71
	s_cbranch_scc1 .Latt_stgB_skip
	s_mul_hi_u32 s49, s50, 0xaaaaaaab
	s_lshr_b32 s49, s49, 1
	s_mul_i32 s49, s49, 0xc000
	s_sub_i32 s49, s31, s49
	s_add_i32 s49, s36, s49
	s_add_i32 s49, s2, s49
	s_lshl_b32 s51, s37, 14
	s_add_i32 s51, s76, s51
	s_mov_b32 m0, s49
	s_add_i32 s50, s51, 0xc000
	global_load_lds_dwordx4 v[114:115], off
	v_lshl_add_u64 v[192:193], v[114:115], 0, s[44:45]
	s_add_i32 m0, s49, 0x2000
	s_nop 0
	global_load_lds_dwordx4 v[192:193], off
	s_mov_b32 m0, s50
	s_nop 0
	global_load_lds_dwordx4 v[118:119], off
	s_add_i32 m0, s51, 0xe000
	s_nop 0
	global_load_lds_dwordx4 v[116:117], off
.Latt_stgB_skip:
	ds_read_b128 v[90:93], v131 offset:50176
	s_waitcnt lgkmcnt(1)
	v_mfma_f32_16x16x32_bf16 v[46:49], v[176:179], v[14:17], v[46:49]
	ds_read_b128 v[176:179], v131 offset:58368
	v_exp_f32_e32 v98, v164
	v_exp_f32_e32 v99, v165
	v_exp_f32_e32 v100, v166
	v_exp_f32_e32 v101, v167
	ds_read_b128 v[180:183], v131 offset:52224
	v_mfma_f32_16x16x32_bf16 v[38:41], v[82:85], v[14:17], v[38:41]
	v_max3_f32 v194, v22, v23, v24
	v_max3_f32 v194, v194, v25, v26
	v_max3_f32 v194, v194, v27, v28
	v_max3_f32 v194, v194, v29, v195
	v_mfma_f32_16x16x32_bf16 v[2:5], v[154:157], v[14:17], v[2:5]
	v_exp_f32_e32 v102, v168
	v_exp_f32_e32 v103, v169
	v_exp_f32_e32 v104, v170
	v_exp_f32_e32 v105, v171
	ds_read_b128 v[94:97], v131 offset:60416
	s_waitcnt lgkmcnt(2)
	v_mfma_f32_16x16x32_bf16 v[30:33], v[90:93], v[184:187], v[30:33]
	ds_read_b128 v[90:93], v131 offset:62464
	v_mov_b32_e32 v158, v194
	s_nop 1
	v_permlane16_swap_b32_e32 v194, v158
	v_max_f32_e32 v194, v194, v158
	s_waitcnt lgkmcnt(2)
	v_mfma_f32_16x16x32_bf16 v[50:53], v[180:183], v[184:187], v[50:53]
	ds_read_b128 v[180:183], v131 offset:64512
	v_exp_f32_e32 v133, v172
	v_exp_f32_e32 v134, v173
	v_exp_f32_e32 v135, v174
	v_exp_f32_e32 v136, v175
	v_mfma_f32_16x16x32_bf16 v[42:45], v[78:81], v[184:187], v[42:45]
	v_mov_b32_e32 v158, v194
	s_nop 1
	v_permlane32_swap_b32_e32 v194, v158
	v_max_f32_e32 v194, v194, v158
	v_mfma_f32_16x16x32_bf16 v[34:37], v[86:89], v[184:187], v[34:37]
	v_cvt_pk_bf16_f32 v14, v145, v146
	v_cvt_pk_bf16_f32 v15, v147, v148
	v_cvt_pk_bf16_f32 v16, v98, v99
	v_cvt_pk_bf16_f32 v17, v100, v101
	v_cvt_pk_bf16_f32 v6, v102, v103
	v_cvt_pk_bf16_f32 v7, v104, v105
	v_cvt_pk_bf16_f32 v8, v133, v134
	v_cvt_pk_bf16_f32 v9, v135, v136
	v_mfma_f32_16x16x32_bf16 v[58:61], v[176:179], v[184:187], v[58:61]
	s_waitcnt lgkmcnt(0)
	v_mfma_f32_16x16x32_bf16 v[54:57], v[94:97], v[184:187], v[54:57]
	v_mfma_f32_16x16x32_bf16 v[46:49], v[90:93], v[184:187], v[46:49]
	v_mfma_f32_16x16x32_bf16 v[38:41], v[180:183], v[184:187], v[38:41]
	v_mfma_f32_16x16x32_bf16 v[2:5], v[154:157], v[184:187], v[2:5]
	s_andn2_b64 vcc, exec, s[34:35]
	s_cbranch_vccnz .Latt_B_1331
	v_sub_f32_e32 v74, v74, v132
	v_sub_f32_e32 v75, v75, v132
	v_sub_f32_e32 v76, v76, v132
	v_sub_f32_e32 v77, v77, v132
	v_sub_f32_e32 v70, v70, v132
	v_sub_f32_e32 v71, v71, v132
	v_sub_f32_e32 v72, v72, v132
	v_sub_f32_e32 v73, v73, v132
	v_sub_f32_e32 v22, v22, v132
	v_sub_f32_e32 v23, v23, v132
	v_sub_f32_e32 v24, v24, v132
	v_sub_f32_e32 v25, v25, v132
	v_sub_f32_e32 v26, v26, v132
	v_sub_f32_e32 v27, v27, v132
	v_sub_f32_e32 v28, v28, v132
	v_sub_f32_e32 v29, v29, v132
	v_sub_f32_e32 v194, v194, v132
	v_pk_mul_f32 v[40:41], v[0:1], v[40:41] op_sel_hi:[0,1]
	v_pk_mul_f32 v[48:49], v[0:1], v[48:49] op_sel_hi:[0,1]
	v_pk_mul_f32 v[56:57], v[0:1], v[56:57] op_sel_hi:[0,1]
	v_pk_mul_f32 v[60:61], v[0:1], v[60:61] op_sel_hi:[0,1]
	v_pk_mul_f32 v[36:37], v[0:1], v[36:37] op_sel_hi:[0,1]
	v_pk_mul_f32 v[44:45], v[0:1], v[44:45] op_sel_hi:[0,1]
	v_pk_mul_f32 v[52:53], v[0:1], v[52:53] op_sel_hi:[0,1]
	v_pk_mul_f32 v[32:33], v[0:1], v[32:33] op_sel_hi:[0,1]
	v_pk_mul_f32 v[38:39], v[0:1], v[38:39] op_sel_hi:[0,1]
	v_pk_mul_f32 v[46:47], v[0:1], v[46:47] op_sel_hi:[0,1]
	v_pk_mul_f32 v[54:55], v[0:1], v[54:55] op_sel_hi:[0,1]
	v_pk_mul_f32 v[58:59], v[0:1], v[58:59] op_sel_hi:[0,1]
	v_pk_mul_f32 v[34:35], v[0:1], v[34:35] op_sel_hi:[0,1]
	v_pk_mul_f32 v[42:43], v[0:1], v[42:43] op_sel_hi:[0,1]
	v_pk_mul_f32 v[50:51], v[0:1], v[50:51] op_sel_hi:[0,1]
	v_pk_mul_f32 v[30:31], v[0:1], v[30:31] op_sel_hi:[0,1]
	v_pk_mul_f32 v[4:5], v[0:1], v[4:5] op_sel_hi:[0,1]
	v_pk_mul_f32 v[2:3], v[0:1], v[2:3] op_sel_hi:[0,1]
